# L1-P3 short-conv: all 30 operand loads of a tile issued together at the tile top (was 18 serialized round trips); FFT stage barrier moved down to the first LDS write
# speedup vs baseline: 1.0181x; 1.0181x over previous
.LBB0_1295:
	s_and_b32 s16, s4, 0xffffffc0
	s_and_b32 s17, s18, 0x7c0
	v_add_u32_e32 v60, s16, v5
	v_or_b32_e32 v0, s17, v54
	v_mad_i64_i32 v[32:33], s[0:1], v60, s20, v[8:9]
	v_lshlrev_b32_e32 v10, 1, v0
	v_mov_b32_e32 v11, v7
	v_lshlrev_b32_e32 v6, 2, v0
	v_mul_u32_u24_e32 v154, 0x3000, v60
	v_max_i32_e32 v155, 1, v60
	v_add_u32_e32 v154, v154, v10
	v_add_u32_e32 v155, -1, v155
	v_mul_u32_u24_e32 v155, 0x3000, v155
	v_add_u32_e32 v155, v155, v10
	global_load_dwordx2 v[70:71], v155, s[48:49]
	v_add_u32_e32 v156, 0x1000, v155
	global_load_dwordx2 v[72:73], v156, s[48:49]
	v_add_u32_e32 v157, 0x2000, v155
	global_load_dwordx2 v[74:75], v157, s[48:49]
	global_load_dwordx2 v[76:77], v154, s[48:49]
	v_add_u32_e32 v158, 0x1000, v154
	global_load_dwordx2 v[78:79], v158, s[48:49]
	v_add_u32_e32 v159, 0x2000, v154
	global_load_dwordx2 v[80:81], v159, s[48:49]
	v_add_u32_e32 v160, 0x3000, v154
	global_load_dwordx2 v[82:83], v160, s[48:49]
	v_add_u32_e32 v161, 0x4000, v154
	global_load_dwordx2 v[84:85], v161, s[48:49]
	v_add_u32_e32 v162, 0x5000, v154
	global_load_dwordx2 v[86:87], v162, s[48:49]
	v_add_u32_e32 v163, 0x5d000, v154
	global_load_dwordx2 v[88:89], v163, s[48:49]
	v_add_u32_e32 v164, 0x5e000, v154
	global_load_dwordx2 v[90:91], v164, s[48:49]
	v_add_u32_e32 v165, 0x5f000, v154
	global_load_dwordx2 v[92:93], v165, s[48:49]
	v_add_u32_e32 v166, 0x60000, v154
	global_load_dwordx2 v[94:95], v166, s[48:49]
	v_add_u32_e32 v167, 0x61000, v154
	global_load_dwordx2 v[96:97], v167, s[48:49]
	v_add_u32_e32 v168, 0x62000, v154
	global_load_dwordx2 v[98:99], v168, s[48:49]
	v_add_u32_e32 v169, 0x63000, v154
	global_load_dwordx2 v[100:101], v169, s[48:49]
	v_add_u32_e32 v170, 0x64000, v154
	global_load_dwordx2 v[102:103], v170, s[48:49]
	v_add_u32_e32 v171, 0x65000, v154
	global_load_dwordx2 v[104:105], v171, s[48:49]
	v_add_u32_e32 v172, 0x2000, v6
	v_add_u32_e32 v173, 0x4000, v6
	global_load_dwordx4 v[118:121], v6, s[12:13]
	global_load_dwordx4 v[122:125], v172, s[12:13]
	global_load_dwordx4 v[126:129], v173, s[12:13]
	global_load_dwordx4 v[142:145], v6, s[10:11]
	global_load_dwordx4 v[146:149], v172, s[10:11]
	global_load_dwordx4 v[150:153], v173, s[10:11]
	global_load_dwordx4 v[130:133], v6, s[14:15]
	global_load_dwordx4 v[134:137], v172, s[14:15]
	global_load_dwordx4 v[138:141], v173, s[14:15]
	global_load_dwordx4 v[106:109], v6, s[8:9]
	global_load_dwordx4 v[110:113], v172, s[8:9]
	global_load_dwordx4 v[114:117], v173, s[8:9]
	s_waitcnt vmcnt(0)
	v_lshl_add_u64 v[0:1], v[32:33], 0, v[10:11]
	v_mov_b64_e32 v[26:27], v[76:77]
	v_lshl_add_u64 v[20:21], s[12:13], 0, v[6:7]
	v_lshl_add_u64 v[24:25], s[10:11], 0, v[6:7]
	v_mov_b64_e32 v[12:13], v[118:119]
	v_mov_b64_e32 v[14:15], v[120:121]
	v_mov_b64_e32 v[16:17], v[142:143]
	v_mov_b64_e32 v[18:19], v[144:145]
	v_lshl_add_u64 v[22:23], s[14:15], 0, v[6:7]
	v_mov_b64_e32 v[0:1], v[130:131]
	v_mov_b64_e32 v[2:3], v[132:133]
	v_add_u32_e32 v28, -1, v60
	v_mad_u64_u32 v[42:43], s[0:1], v28, s20, v[8:9]
	v_cmp_lt_i32_e32 vcc, 0, v60
	s_waitcnt vmcnt(0)
	v_lshlrev_b32_e32 v28, 16, v26
	v_and_b32_e32 v29, 0xffff0000, v26
	v_lshlrev_b32_e32 v26, 16, v27
	v_and_b32_e32 v27, 0xffff0000, v27
	s_waitcnt lgkmcnt(0)
	v_pk_fma_f32 v[38:39], v[14:15], v[26:27], v[18:19]
	v_pk_fma_f32 v[40:41], v[12:13], v[28:29], v[16:17]
	s_and_saveexec_b64 s[0:1], vcc
	s_cbranch_execz .LBB0_1297
	v_lshl_add_u64 v[12:13], v[42:43], 0, v[10:11]
	v_mov_b64_e32 v[16:17], v[70:71]
	v_lshl_add_u64 v[12:13], s[8:9], 0, v[6:7]
	v_mov_b64_e32 v[12:13], v[106:107]
	v_mov_b64_e32 v[14:15], v[108:109]
	s_waitcnt vmcnt(0)
	v_lshlrev_b32_e32 v18, 16, v16
	v_and_b32_e32 v19, 0xffff0000, v16
	v_lshlrev_b32_e32 v16, 16, v17
	v_and_b32_e32 v17, 0xffff0000, v17
	s_waitcnt lgkmcnt(0)
	v_pk_fma_f32 v[38:39], v[14:15], v[16:17], v[38:39]
	v_pk_fma_f32 v[40:41], v[12:13], v[18:19], v[40:41]
.LBB0_1297:
	s_or_b64 exec, exec, s[0:1]
	v_add_u32_e32 v11, 1, v60
	v_mov_b64_e32 v[12:13], s[48:49]
	v_cmp_gt_i32_e64 s[6:7], s21, v60
	v_mad_i64_i32 v[44:45], s[0:1], v11, s20, v[12:13]
	s_and_saveexec_b64 s[0:1], s[6:7]
	s_cbranch_execz .LBB0_1299
	v_mov_b32_e32 v11, v7
	v_lshl_add_u64 v[12:13], v[44:45], 0, v[10:11]
	v_mov_b64_e32 v[12:13], v[82:83]
	s_waitcnt vmcnt(0)
	v_lshlrev_b32_e32 v14, 16, v12
	v_and_b32_e32 v15, 0xffff0000, v12
	v_lshlrev_b32_e32 v12, 16, v13
	v_and_b32_e32 v13, 0xffff0000, v13
	v_pk_fma_f32 v[38:39], v[2:3], v[12:13], v[38:39]
	v_pk_fma_f32 v[40:41], v[0:1], v[14:15], v[40:41]
.LBB0_1299:
	s_or_b64 exec, exec, s[0:1]
	v_or_b32_e32 v0, s17, v57
	v_lshlrev_b32_e32 v12, 1, v0
	v_mov_b32_e32 v13, v7
	v_lshlrev_b32_e32 v16, 2, v0
	v_mov_b32_e32 v17, v7
	v_lshl_add_u64 v[0:1], v[32:33], 0, v[12:13]
	v_mov_b64_e32 v[14:15], v[78:79]
	v_lshl_add_u64 v[26:27], s[12:13], 0, v[16:17]
	v_lshl_add_u64 v[30:31], s[10:11], 0, v[16:17]
	v_mov_b64_e32 v[34:35], v[122:123]
	v_mov_b64_e32 v[36:37], v[124:125]
	v_mov_b64_e32 v[48:49], v[146:147]
	v_mov_b64_e32 v[50:51], v[148:149]
	v_lshl_add_u64 v[28:29], s[14:15], 0, v[16:17]
	v_mov_b64_e32 v[0:1], v[134:135]
	v_mov_b64_e32 v[2:3], v[136:137]
	s_waitcnt vmcnt(0)
	v_lshlrev_b32_e32 v18, 16, v14
	v_and_b32_e32 v19, 0xffff0000, v14
	v_lshlrev_b32_e32 v14, 16, v15
	v_and_b32_e32 v15, 0xffff0000, v15
	s_waitcnt lgkmcnt(0)
	v_pk_fma_f32 v[46:47], v[36:37], v[14:15], v[50:51]
	v_pk_fma_f32 v[48:49], v[34:35], v[18:19], v[48:49]
	s_and_saveexec_b64 s[0:1], vcc
	s_cbranch_execz .LBB0_1301
	v_lshl_add_u64 v[14:15], v[42:43], 0, v[12:13]
	v_mov_b64_e32 v[14:15], v[72:73]
	v_lshl_add_u64 v[18:19], s[8:9], 0, v[16:17]
	v_mov_b64_e32 v[34:35], v[110:111]
	v_mov_b64_e32 v[36:37], v[112:113]
	s_waitcnt vmcnt(0)
	v_lshlrev_b32_e32 v18, 16, v14
	v_and_b32_e32 v19, 0xffff0000, v14
	v_lshlrev_b32_e32 v14, 16, v15
	v_and_b32_e32 v15, 0xffff0000, v15
	s_waitcnt lgkmcnt(0)
	v_pk_fma_f32 v[46:47], v[36:37], v[14:15], v[46:47]
	v_pk_fma_f32 v[48:49], v[34:35], v[18:19], v[48:49]
.LBB0_1301:
	s_or_b64 exec, exec, s[0:1]
	s_and_saveexec_b64 s[0:1], s[6:7]
	s_cbranch_execz .LBB0_1303
	v_mov_b32_e32 v13, v7
	v_lshl_add_u64 v[14:15], v[44:45], 0, v[12:13]
	v_mov_b64_e32 v[14:15], v[84:85]
	s_waitcnt vmcnt(0)
	v_lshlrev_b32_e32 v18, 16, v14
	v_and_b32_e32 v19, 0xffff0000, v14
	v_lshlrev_b32_e32 v14, 16, v15
	v_and_b32_e32 v15, 0xffff0000, v15
	v_pk_fma_f32 v[46:47], v[2:3], v[14:15], v[46:47]
	v_pk_fma_f32 v[48:49], v[0:1], v[18:19], v[48:49]
.LBB0_1303:
	s_or_b64 exec, exec, s[0:1]
	v_or_b32_e32 v0, s17, v58
	v_lshlrev_b32_e32 v14, 1, v0
	v_mov_b32_e32 v15, v7
	v_lshlrev_b32_e32 v18, 2, v0
	v_mov_b32_e32 v19, v7
	v_lshl_add_u64 v[0:1], v[32:33], 0, v[14:15]
	v_mov_b64_e32 v[50:51], v[80:81]
	v_lshl_add_u64 v[32:33], s[12:13], 0, v[18:19]
	v_lshl_add_u64 v[36:37], s[10:11], 0, v[18:19]
	v_mov_b64_e32 v[62:63], v[126:127]
	v_mov_b64_e32 v[64:65], v[128:129]
	v_mov_b64_e32 v[66:67], v[150:151]
	v_mov_b64_e32 v[68:69], v[152:153]
	v_lshl_add_u64 v[34:35], s[14:15], 0, v[18:19]
	v_mov_b64_e32 v[0:1], v[138:139]
	v_mov_b64_e32 v[2:3], v[140:141]
	s_waitcnt vmcnt(0)
	v_lshlrev_b32_e32 v52, 16, v50
	v_and_b32_e32 v53, 0xffff0000, v50
	v_lshlrev_b32_e32 v50, 16, v51
	v_and_b32_e32 v51, 0xffff0000, v51
	s_waitcnt lgkmcnt(0)
	v_pk_fma_f32 v[50:51], v[64:65], v[50:51], v[68:69]
	v_pk_fma_f32 v[52:53], v[62:63], v[52:53], v[66:67]
	s_and_saveexec_b64 s[0:1], vcc
	s_cbranch_execz .LBB0_1305
	v_lshl_add_u64 v[42:43], v[42:43], 0, v[14:15]
	v_mov_b64_e32 v[42:43], v[74:75]
	v_lshl_add_u64 v[62:63], s[8:9], 0, v[18:19]
	v_mov_b64_e32 v[62:63], v[114:115]
	v_mov_b64_e32 v[64:65], v[116:117]
	s_waitcnt vmcnt(0)
	v_lshlrev_b32_e32 v66, 16, v42
	v_and_b32_e32 v67, 0xffff0000, v42
	v_lshlrev_b32_e32 v42, 16, v43
	v_and_b32_e32 v43, 0xffff0000, v43
	s_waitcnt lgkmcnt(0)
	v_pk_fma_f32 v[50:51], v[64:65], v[42:43], v[50:51]
	v_pk_fma_f32 v[52:53], v[62:63], v[66:67], v[52:53]
.LBB0_1305:
	s_or_b64 exec, exec, s[0:1]
	s_and_saveexec_b64 s[0:1], s[6:7]
	s_cbranch_execz .LBB0_1307
	v_mov_b32_e32 v15, v7
	v_lshl_add_u64 v[42:43], v[44:45], 0, v[14:15]
	v_mov_b64_e32 v[42:43], v[86:87]
	s_waitcnt vmcnt(0)
	v_lshlrev_b32_e32 v44, 16, v42
	v_and_b32_e32 v45, 0xffff0000, v42
	v_lshlrev_b32_e32 v42, 16, v43
	v_and_b32_e32 v43, 0xffff0000, v43
	v_pk_fma_f32 v[50:51], v[2:3], v[42:43], v[50:51]
	v_pk_fma_f32 v[52:53], v[0:1], v[44:45], v[52:53]
.LBB0_1307:
	s_or_b64 exec, exec, s[0:1]
	ds_write2_b32 v59, v40, v41 offset1:65
	v_add_u32_e32 v13, 32, v60
	v_mov_b64_e32 v[40:41], s[48:49]
	v_mul_f32_e32 v0, v52, v48
	v_mul_f32_e32 v1, v53, v49
	v_add_u32_e32 v42, 0x4000, v59
	ds_write2_b32 v59, v38, v39 offset0:130 offset1:195
	v_mad_i64_i32 v[38:39], s[0:1], v13, s20, v[40:41]
	v_mov_b32_e32 v11, v7
	ds_write2_b32 v42, v0, v1 offset0:64 offset1:129
	v_lshl_add_u64 v[0:1], v[38:39], 0, v[10:11]
	v_mul_f32_e32 v2, v50, v46
	v_mul_f32_e32 v3, v51, v47
	v_mov_b64_e32 v[52:53], v[94:95]
	v_add_u32_e32 v43, 0x4200, v59
	ds_write2_b32 v43, v2, v3 offset0:66 offset1:131
	v_mov_b64_e32 v[44:45], v[142:143]
	v_mov_b64_e32 v[46:47], v[144:145]
	v_mov_b64_e32 v[48:49], v[118:119]
	v_mov_b64_e32 v[50:51], v[120:121]
	v_mov_b64_e32 v[0:1], v[130:131]
	v_mov_b64_e32 v[2:3], v[132:133]
	v_add_u32_e32 v15, 31, v60
	v_cmp_lt_i32_e32 vcc, 0, v13
	v_mad_u64_u32 v[24:25], s[0:1], v15, s20, v[40:41]
	s_waitcnt vmcnt(0)
	v_lshlrev_b32_e32 v22, 16, v52
	v_and_b32_e32 v23, 0xffff0000, v52
	v_lshlrev_b32_e32 v20, 16, v53
	v_and_b32_e32 v21, 0xffff0000, v53
	s_waitcnt lgkmcnt(0)
	v_pk_fma_f32 v[20:21], v[50:51], v[20:21], v[46:47]
	v_pk_fma_f32 v[22:23], v[48:49], v[22:23], v[44:45]
	s_and_saveexec_b64 s[0:1], vcc
	s_cbranch_execz .LBB0_1309
	v_lshl_add_u64 v[40:41], v[24:25], 0, v[10:11]
	v_mov_b64_e32 v[40:41], v[88:89]
	v_lshl_add_u64 v[44:45], s[8:9], 0, v[6:7]
	v_mov_b64_e32 v[44:45], v[106:107]
	v_mov_b64_e32 v[46:47], v[108:109]
	s_waitcnt vmcnt(0)
	v_lshlrev_b32_e32 v48, 16, v40
	v_and_b32_e32 v49, 0xffff0000, v40
	v_lshlrev_b32_e32 v40, 16, v41
	v_and_b32_e32 v41, 0xffff0000, v41
	s_waitcnt lgkmcnt(0)
	v_pk_fma_f32 v[20:21], v[46:47], v[40:41], v[20:21]
	v_pk_fma_f32 v[22:23], v[44:45], v[48:49], v[22:23]
.LBB0_1309:
	s_or_b64 exec, exec, s[0:1]
	v_add_u32_e32 v6, 1, v13
	v_mov_b64_e32 v[40:41], s[48:49]
	v_cmp_gt_i32_e64 s[6:7], s21, v13
	v_mad_i64_i32 v[40:41], s[0:1], v6, s20, v[40:41]
	s_and_saveexec_b64 s[0:1], s[6:7]
	s_cbranch_execz .LBB0_1311
	v_mov_b32_e32 v11, v7
	v_lshl_add_u64 v[10:11], v[40:41], 0, v[10:11]
	v_mov_b64_e32 v[10:11], v[100:101]
	s_waitcnt vmcnt(0)
	v_lshlrev_b32_e32 v44, 16, v10
	v_and_b32_e32 v45, 0xffff0000, v10
	v_lshlrev_b32_e32 v10, 16, v11
	v_and_b32_e32 v11, 0xffff0000, v11
	v_pk_fma_f32 v[20:21], v[2:3], v[10:11], v[20:21]
	v_pk_fma_f32 v[22:23], v[0:1], v[44:45], v[22:23]
.LBB0_1311:
	s_or_b64 exec, exec, s[0:1]
	v_mov_b32_e32 v13, v7
	v_lshl_add_u64 v[0:1], v[38:39], 0, v[12:13]
	v_mov_b64_e32 v[10:11], v[96:97]
	v_mov_b64_e32 v[44:45], v[146:147]
	v_mov_b64_e32 v[46:47], v[148:149]
	v_mov_b64_e32 v[48:49], v[122:123]
	v_mov_b64_e32 v[50:51], v[124:125]
	s_nop 0
	v_mov_b64_e32 v[0:1], v[134:135]
	v_mov_b64_e32 v[2:3], v[136:137]
	s_waitcnt vmcnt(0)
	v_lshlrev_b32_e32 v26, 16, v10
	v_and_b32_e32 v27, 0xffff0000, v10
	v_lshlrev_b32_e32 v10, 16, v11
	v_and_b32_e32 v11, 0xffff0000, v11
	s_waitcnt lgkmcnt(0)
	v_pk_fma_f32 v[10:11], v[50:51], v[10:11], v[46:47]
	v_pk_fma_f32 v[26:27], v[48:49], v[26:27], v[44:45]
	s_and_saveexec_b64 s[0:1], vcc
	s_cbranch_execz .LBB0_1313
	v_lshl_add_u64 v[28:29], v[24:25], 0, v[12:13]
	v_mov_b32_e32 v17, v7
	v_mov_b64_e32 v[44:45], v[90:91]
	v_lshl_add_u64 v[16:17], s[8:9], 0, v[16:17]
	v_mov_b64_e32 v[28:29], v[110:111]
	v_mov_b64_e32 v[30:31], v[112:113]
	s_waitcnt vmcnt(0)
	v_lshlrev_b32_e32 v16, 16, v44
	v_and_b32_e32 v17, 0xffff0000, v44
	v_lshlrev_b32_e32 v44, 16, v45
	v_and_b32_e32 v45, 0xffff0000, v45
	s_waitcnt lgkmcnt(0)
	v_pk_fma_f32 v[10:11], v[30:31], v[44:45], v[10:11]
	v_pk_fma_f32 v[26:27], v[28:29], v[16:17], v[26:27]
.LBB0_1313:
	s_or_b64 exec, exec, s[0:1]
	s_and_saveexec_b64 s[0:1], s[6:7]
	s_cbranch_execz .LBB0_1315
	v_mov_b32_e32 v13, v7
	v_lshl_add_u64 v[12:13], v[40:41], 0, v[12:13]
	v_mov_b64_e32 v[12:13], v[102:103]
	s_waitcnt vmcnt(0)
	v_lshlrev_b32_e32 v16, 16, v12
	v_and_b32_e32 v17, 0xffff0000, v12
	v_lshlrev_b32_e32 v12, 16, v13
	v_and_b32_e32 v13, 0xffff0000, v13
	v_pk_fma_f32 v[10:11], v[2:3], v[12:13], v[10:11]
	v_pk_fma_f32 v[26:27], v[0:1], v[16:17], v[26:27]
.LBB0_1315:
	s_or_b64 exec, exec, s[0:1]
	v_mov_b32_e32 v15, v7
	v_lshl_add_u64 v[0:1], v[38:39], 0, v[14:15]
	v_mov_b64_e32 v[12:13], v[98:99]
	v_mov_b64_e32 v[28:29], v[150:151]
	v_mov_b64_e32 v[30:31], v[152:153]
	s_nop 0
	v_mov_b64_e32 v[36:37], v[126:127]
	v_mov_b64_e32 v[38:39], v[128:129]
	v_mov_b64_e32 v[0:1], v[138:139]
	v_mov_b64_e32 v[2:3], v[140:141]
	s_waitcnt vmcnt(0)
	v_lshlrev_b32_e32 v16, 16, v12
	v_and_b32_e32 v17, 0xffff0000, v12
	v_lshlrev_b32_e32 v12, 16, v13
	v_and_b32_e32 v13, 0xffff0000, v13
	s_waitcnt lgkmcnt(0)
	v_pk_fma_f32 v[12:13], v[38:39], v[12:13], v[30:31]
	v_pk_fma_f32 v[16:17], v[36:37], v[16:17], v[28:29]
	s_and_saveexec_b64 s[0:1], vcc
	s_cbranch_execz .LBB0_1317
	v_lshl_add_u64 v[24:25], v[24:25], 0, v[14:15]
	v_mov_b32_e32 v19, v7
	v_mov_b64_e32 v[24:25], v[92:93]
	v_lshl_add_u64 v[18:19], s[8:9], 0, v[18:19]
	v_mov_b64_e32 v[28:29], v[114:115]
	v_mov_b64_e32 v[30:31], v[116:117]
	s_waitcnt vmcnt(0)
	v_lshlrev_b32_e32 v18, 16, v24
	v_and_b32_e32 v19, 0xffff0000, v24
	v_lshlrev_b32_e32 v24, 16, v25
	v_and_b32_e32 v25, 0xffff0000, v25
	s_waitcnt lgkmcnt(0)
	v_pk_fma_f32 v[12:13], v[30:31], v[24:25], v[12:13]
	v_pk_fma_f32 v[16:17], v[28:29], v[18:19], v[16:17]
.LBB0_1317:
	s_or_b64 exec, exec, s[0:1]
	s_and_saveexec_b64 s[0:1], s[6:7]
	s_cbranch_execz .LBB0_1294
	v_mov_b32_e32 v15, v7
	v_lshl_add_u64 v[14:15], v[40:41], 0, v[14:15]
	v_mov_b64_e32 v[14:15], v[104:105]
	s_waitcnt vmcnt(0)
	v_lshlrev_b32_e32 v18, 16, v14
	v_and_b32_e32 v19, 0xffff0000, v14
	v_lshlrev_b32_e32 v14, 16, v15
	v_and_b32_e32 v15, 0xffff0000, v15
	v_pk_fma_f32 v[12:13], v[2:3], v[14:15], v[12:13]
	v_pk_fma_f32 v[16:17], v[0:1], v[18:19], v[16:17]
	s_branch .LBB0_1294

.LBB0_1393:
	s_sub_i32 s1, 0, s0
	v_and_b32_e32 v184, s1, v32
	ds_read2st64_b64 v[0:3], v145 offset1:8
	ds_read2st64_b64 v[4:7], v145 offset0:32 offset1:40
	ds_read2st64_b64 v[16:19], v145 offset0:64 offset1:72
	ds_read2st64_b64 v[20:23], v145 offset0:96 offset1:104
	ds_read_b64 v[126:127], v33
	ds_read_b64 v[130:131], v146
	ds_read_b64 v[112:113], v148
	ds_read_b64 v[116:117], v149
	ds_read_b64 v[136:137], v156
	ds_read_b64 v[138:139], v157
	ds_read_b64 v[118:119], v158
	ds_read_b64 v[122:123], v159
	ds_read2st64_b64 v[8:11], v145 offset0:16 offset1:24
	ds_read2st64_b64 v[12:15], v145 offset0:48 offset1:56
	ds_read2st64_b64 v[24:27], v145 offset0:80 offset1:88
	ds_read2st64_b64 v[28:31], v145 offset0:112 offset1:120
	ds_read_b64 v[132:133], v151
	ds_read_b64 v[134:135], v152
	ds_read_b64 v[114:115], v154
	ds_read_b64 v[120:121], v155
	ds_read_b64 v[140:141], v160
	ds_read_b64 v[142:143], v161
	ds_read_b64 v[124:125], v162
	ds_read_b64 v[128:129], v163
	v_and_b32_e32 v185, s1, v147
	v_lshl_add_u32 v184, v184, 3, s29
	s_waitcnt lgkmcnt(0)
	v_lshl_add_u32 v196, v185, 3, s29
	ds_read_b64 v[184:185], v184
	v_and_b32_e32 v186, s1, v150
	v_and_b32_e32 v187, s1, v153
	v_lshl_add_u32 v197, v186, 3, s29
	v_lshl_add_u32 v198, v187, 3, s29
	ds_read_b64 v[200:201], v196
	ds_read_b64 v[202:203], v197
	ds_read_b64 v[204:205], v198
	v_pk_add_f32 v[186:187], v[0:1], v[16:17]
	v_pk_add_f32 v[188:189], v[0:1], v[16:17] neg_lo:[0,1] neg_hi:[0,1]
	v_pk_add_f32 v[0:1], v[4:5], v[20:21]
	v_pk_add_f32 v[4:5], v[4:5], v[20:21] neg_lo:[0,1] neg_hi:[0,1]
	v_pk_add_f32 v[16:17], v[126:127], v[130:131]
	v_pk_add_f32 v[126:127], v[126:127], v[130:131] neg_lo:[0,1] neg_hi:[0,1]
	v_pk_add_f32 v[20:21], v[136:137], v[138:139]
	v_pk_add_f32 v[130:131], v[136:137], v[138:139] neg_lo:[0,1] neg_hi:[0,1]
	v_pk_add_f32 v[136:137], v[2:3], v[18:19]
	v_pk_add_f32 v[2:3], v[2:3], v[18:19] neg_lo:[0,1] neg_hi:[0,1]
	v_pk_add_f32 v[18:19], v[6:7], v[22:23]
	v_pk_add_f32 v[6:7], v[6:7], v[22:23] neg_lo:[0,1] neg_hi:[0,1]
	v_pk_add_f32 v[22:23], v[112:113], v[116:117]
	v_pk_add_f32 v[112:113], v[112:113], v[116:117] neg_lo:[0,1] neg_hi:[0,1]
	v_pk_add_f32 v[116:117], v[118:119], v[122:123]
	v_pk_add_f32 v[118:119], v[118:119], v[122:123] neg_lo:[0,1] neg_hi:[0,1]
	v_pk_add_f32 v[122:123], v[8:9], v[24:25]
	v_pk_add_f32 v[138:139], v[8:9], v[24:25] neg_lo:[0,1] neg_hi:[0,1]
	v_pk_add_f32 v[24:25], v[12:13], v[28:29]
	v_pk_add_f32 v[28:29], v[12:13], v[28:29] neg_lo:[0,1] neg_hi:[0,1]
	v_pk_add_f32 v[190:191], v[132:133], v[134:135]
	v_pk_add_f32 v[132:133], v[132:133], v[134:135] neg_lo:[0,1] neg_hi:[0,1]
	v_pk_add_f32 v[134:135], v[140:141], v[142:143]
	v_pk_add_f32 v[140:141], v[140:141], v[142:143] neg_lo:[0,1] neg_hi:[0,1]
	v_pk_add_f32 v[142:143], v[10:11], v[26:27]
	v_pk_add_f32 v[10:11], v[10:11], v[26:27] neg_lo:[0,1] neg_hi:[0,1]
	v_pk_add_f32 v[26:27], v[14:15], v[30:31]
	v_pk_add_f32 v[14:15], v[14:15], v[30:31] neg_lo:[0,1] neg_hi:[0,1]
	v_pk_add_f32 v[30:31], v[114:115], v[120:121]
	v_pk_add_f32 v[114:115], v[114:115], v[120:121] neg_lo:[0,1] neg_hi:[0,1]
	v_pk_add_f32 v[120:121], v[124:125], v[128:129]
	v_pk_add_f32 v[124:125], v[124:125], v[128:129] neg_lo:[0,1] neg_hi:[0,1]
	v_pk_mul_f32 v[128:129], v[4:5], s[58:59]
	v_pk_add_f32 v[192:193], v[186:187], v[0:1] neg_lo:[0,1] neg_hi:[0,1]
	v_pk_add_f32 v[0:1], v[186:187], v[0:1]
	v_pk_add_f32 v[186:187], v[16:17], v[20:21] neg_lo:[0,1] neg_hi:[0,1]
	v_pk_add_f32 v[4:5], v[16:17], v[20:21]
	v_pk_add_f32 v[194:195], v[136:137], v[18:19] neg_lo:[0,1] neg_hi:[0,1]
	v_pk_add_f32 v[8:9], v[136:137], v[18:19]
	v_pk_mul_f32 v[18:19], v[118:119], s[58:59]
	v_pk_add_f32 v[118:119], v[22:23], v[116:117] neg_lo:[0,1] neg_hi:[0,1]
	v_pk_add_f32 v[12:13], v[22:23], v[116:117]
	v_pk_mul_f32 v[22:23], v[28:29], s[58:59]
	v_pk_add_f32 v[116:117], v[122:123], v[24:25] neg_lo:[0,1] neg_hi:[0,1]
	v_pk_add_f32 v[16:17], v[122:123], v[24:25]
	v_pk_mul_f32 v[122:123], v[140:141], s[58:59]
	v_pk_mul_f32 v[14:15], v[14:15], s[58:59]
	v_pk_mul_f32 v[130:131], v[130:131], s[58:59]
	v_pk_mul_f32 v[6:7], v[6:7], s[58:59]
	v_pk_add_f32 v[136:137], v[190:191], v[134:135] neg_lo:[0,1] neg_hi:[0,1]
	v_pk_add_f32 v[20:21], v[190:191], v[134:135]
	v_pk_add_f32 v[134:135], v[142:143], v[26:27] neg_lo:[0,1] neg_hi:[0,1]
	v_pk_add_f32 v[24:25], v[142:143], v[26:27]
	v_pk_mul_f32 v[26:27], v[124:125], s[58:59]
	v_pk_add_f32 v[124:125], v[30:31], v[120:121] neg_lo:[0,1] neg_hi:[0,1]
	v_pk_add_f32 v[28:29], v[30:31], v[120:121]
	v_pk_add_f32 v[30:31], v[188:189], v[128:129] op_sel:[0,1] op_sel_hi:[1,0]
	v_pk_add_f32 v[120:121], v[188:189], v[128:129] op_sel:[0,1] op_sel_hi:[1,0] neg_lo:[0,1] neg_hi:[0,1]
	v_pk_add_f32 v[142:143], v[112:113], v[18:19] op_sel:[0,1] op_sel_hi:[1,0]
	v_pk_add_f32 v[18:19], v[112:113], v[18:19] op_sel:[0,1] op_sel_hi:[1,0] neg_lo:[0,1] neg_hi:[0,1]
	v_pk_add_f32 v[112:113], v[138:139], v[22:23] op_sel:[0,1] op_sel_hi:[1,0]
	v_pk_add_f32 v[138:139], v[138:139], v[22:23] op_sel:[0,1] op_sel_hi:[1,0] neg_lo:[0,1] neg_hi:[0,1]
	v_pk_add_f32 v[22:23], v[132:133], v[122:123] op_sel:[0,1] op_sel_hi:[1,0]
	v_pk_add_f32 v[122:123], v[132:133], v[122:123] op_sel:[0,1] op_sel_hi:[1,0] neg_lo:[0,1] neg_hi:[0,1]
	v_pk_add_f32 v[132:133], v[10:11], v[14:15] op_sel:[0,1] op_sel_hi:[1,0]
	v_pk_add_f32 v[188:189], v[10:11], v[14:15] op_sel:[0,1] op_sel_hi:[1,0] neg_lo:[0,1] neg_hi:[0,1]
	s_waitcnt lgkmcnt(0)
	v_xor_b32_e32 v10, 0x80000000, v185
	v_mov_b32_e32 v11, v185
	v_pk_add_f32 v[128:129], v[126:127], v[130:131] op_sel:[0,1] op_sel_hi:[1,0]
	v_pk_add_f32 v[126:127], v[126:127], v[130:131] op_sel:[0,1] op_sel_hi:[1,0] neg_lo:[0,1] neg_hi:[0,1]
	v_pk_add_f32 v[130:131], v[2:3], v[6:7] op_sel:[0,1] op_sel_hi:[1,0]
	v_pk_add_f32 v[140:141], v[2:3], v[6:7] op_sel:[0,1] op_sel_hi:[1,0] neg_lo:[0,1] neg_hi:[0,1]
	v_pk_mul_f32 v[2:3], v[184:185], v[10:11] op_sel:[1,0] op_sel_hi:[0,1]
	v_pk_add_f32 v[190:191], v[114:115], v[26:27] op_sel:[0,1] op_sel_hi:[1,0]
	v_pk_add_f32 v[114:115], v[114:115], v[26:27] op_sel:[0,1] op_sel_hi:[1,0] neg_lo:[0,1] neg_hi:[0,1]
	v_pk_mul_f32 v[6:7], v[10:11], v[30:31] op_sel:[0,1] op_sel_hi:[1,0]
	v_pk_mul_f32 v[14:15], v[10:11], v[128:129] op_sel:[0,1] op_sel_hi:[1,0]
	v_pk_fma_f32 v[26:27], v[184:185], v[184:185], v[2:3] op_sel_hi:[1,0,1]
	v_pk_fma_f32 v[2:3], v[184:185], v[30:31], v[6:7] op_sel_hi:[0,1,1]
	v_pk_fma_f32 v[6:7], v[184:185], v[128:129], v[14:15] op_sel_hi:[0,1,1]
	v_pk_mul_f32 v[10:11], v[10:11], v[26:27] op_sel:[0,1] op_sel_hi:[1,0]
	v_xor_b32_e32 v14, 0x80000000, v27
	v_mov_b32_e32 v15, v27
	s_barrier
	ds_write_b128 v180, v[0:3]
	ds_write_b128 v164, v[4:7]
	v_pk_fma_f32 v[6:7], v[184:185], v[26:27], v[10:11] op_sel_hi:[0,1,1]
	v_pk_mul_f32 v[2:3], v[14:15], v[186:187] op_sel:[0,1] op_sel_hi:[1,0]
	v_xor_b32_e32 v10, 0x80000000, v7
	v_mov_b32_e32 v11, v7
	v_pk_mul_f32 v[0:1], v[14:15], v[192:193] op_sel:[0,1] op_sel_hi:[1,0]
	v_pk_fma_f32 v[4:5], v[26:27], v[186:187], v[2:3] op_sel_hi:[0,1,1]
	v_pk_mul_f32 v[2:3], v[120:121], v[10:11] op_sel:[1,0] op_sel_hi:[0,1]
	v_pk_fma_f32 v[0:1], v[26:27], v[192:193], v[0:1] op_sel_hi:[0,1,1]
	v_pk_mul_f32 v[10:11], v[10:11], v[126:127] op_sel:[0,1] op_sel_hi:[1,0]
	v_pk_fma_f32 v[2:3], v[120:121], v[6:7], v[2:3] op_sel_hi:[1,0,1]
	v_pk_fma_f32 v[6:7], v[6:7], v[126:127], v[10:11] op_sel_hi:[0,1,1]
	ds_write_b128 v180, v[0:3] offset:16
	ds_write_b128 v164, v[4:7] offset:16
	v_mov_b64_e32 v[0:1], v[200:201]
	s_lshl_b32 s0, s0, 2
	s_cmpk_gt_i32 s0, 0x400
	v_xor_b32_e32 v2, 0x80000000, v1
	v_mov_b32_e32 v3, v1
	v_pk_mul_f32 v[4:5], v[0:1], v[2:3] op_sel:[1,0] op_sel_hi:[0,1]
	v_pk_mul_f32 v[6:7], v[2:3], v[130:131] op_sel:[0,1] op_sel_hi:[1,0]
	v_pk_fma_f32 v[4:5], v[0:1], v[0:1], v[4:5] op_sel_hi:[1,0,1]
	v_pk_mul_f32 v[14:15], v[2:3], v[142:143] op_sel:[0,1] op_sel_hi:[1,0]
	v_pk_fma_f32 v[10:11], v[0:1], v[130:131], v[6:7] op_sel_hi:[0,1,1]
	v_pk_mul_f32 v[2:3], v[2:3], v[4:5] op_sel:[0,1] op_sel_hi:[1,0]
	v_pk_fma_f32 v[14:15], v[0:1], v[142:143], v[14:15] op_sel_hi:[0,1,1]
	v_xor_b32_e32 v6, 0x80000000, v5
	v_mov_b32_e32 v7, v5
	ds_write_b128 v165, v[8:11]
	ds_write_b128 v166, v[12:15]
	v_pk_fma_f32 v[8:9], v[0:1], v[4:5], v[2:3] op_sel_hi:[0,1,1]
	v_pk_mul_f32 v[0:1], v[6:7], v[194:195] op_sel:[0,1] op_sel_hi:[1,0]
	v_pk_mul_f32 v[2:3], v[6:7], v[118:119] op_sel:[0,1] op_sel_hi:[1,0]
	v_xor_b32_e32 v6, 0x80000000, v9
	v_mov_b32_e32 v7, v9
	v_pk_fma_f32 v[0:1], v[4:5], v[194:195], v[0:1] op_sel_hi:[0,1,1]
	v_pk_fma_f32 v[4:5], v[4:5], v[118:119], v[2:3] op_sel_hi:[0,1,1]
	v_pk_mul_f32 v[2:3], v[140:141], v[6:7] op_sel:[1,0] op_sel_hi:[0,1]
	v_pk_mul_f32 v[6:7], v[6:7], v[18:19] op_sel:[0,1] op_sel_hi:[1,0]
	v_pk_fma_f32 v[2:3], v[140:141], v[8:9], v[2:3] op_sel_hi:[1,0,1]
	v_pk_fma_f32 v[6:7], v[8:9], v[18:19], v[6:7] op_sel_hi:[0,1,1]
	ds_write_b128 v165, v[0:3] offset:16
	ds_write_b128 v166, v[4:7] offset:16
	v_mov_b64_e32 v[0:1], v[202:203]
	v_xor_b32_e32 v2, 0x80000000, v1
	v_mov_b32_e32 v3, v1
	v_pk_mul_f32 v[4:5], v[0:1], v[2:3] op_sel:[1,0] op_sel_hi:[0,1]
	v_pk_fma_f32 v[4:5], v[0:1], v[0:1], v[4:5] op_sel_hi:[1,0,1]
	v_pk_mul_f32 v[6:7], v[2:3], v[112:113] op_sel:[0,1] op_sel_hi:[1,0]
	v_pk_mul_f32 v[8:9], v[2:3], v[22:23] op_sel:[0,1] op_sel_hi:[1,0]
	v_pk_mul_f32 v[2:3], v[2:3], v[4:5] op_sel:[0,1] op_sel_hi:[1,0]
	v_pk_fma_f32 v[18:19], v[0:1], v[112:113], v[6:7] op_sel_hi:[0,1,1]
	v_pk_fma_f32 v[22:23], v[0:1], v[22:23], v[8:9] op_sel_hi:[0,1,1]
	v_xor_b32_e32 v6, 0x80000000, v5
	v_mov_b32_e32 v7, v5
	v_pk_fma_f32 v[8:9], v[0:1], v[4:5], v[2:3] op_sel_hi:[0,1,1]
	v_pk_mul_f32 v[0:1], v[6:7], v[116:117] op_sel:[0,1] op_sel_hi:[1,0]
	v_pk_mul_f32 v[2:3], v[6:7], v[136:137] op_sel:[0,1] op_sel_hi:[1,0]
	v_xor_b32_e32 v6, 0x80000000, v9
	v_mov_b32_e32 v7, v9
	v_pk_fma_f32 v[0:1], v[4:5], v[116:117], v[0:1] op_sel_hi:[0,1,1]
	v_pk_fma_f32 v[4:5], v[4:5], v[136:137], v[2:3] op_sel_hi:[0,1,1]
	v_pk_mul_f32 v[2:3], v[138:139], v[6:7] op_sel:[1,0] op_sel_hi:[0,1]
	v_pk_mul_f32 v[6:7], v[6:7], v[122:123] op_sel:[0,1] op_sel_hi:[1,0]
	v_pk_fma_f32 v[2:3], v[138:139], v[8:9], v[2:3] op_sel_hi:[1,0,1]
	ds_write_b128 v167, v[16:19]
	ds_write_b128 v168, v[20:23]
	v_pk_fma_f32 v[6:7], v[8:9], v[122:123], v[6:7] op_sel_hi:[0,1,1]
	ds_write_b128 v167, v[0:3] offset:16
	ds_write_b128 v168, v[4:7] offset:16
	v_mov_b64_e32 v[0:1], v[204:205]
	v_xor_b32_e32 v2, 0x80000000, v1
	v_mov_b32_e32 v3, v1
	v_pk_mul_f32 v[4:5], v[0:1], v[2:3] op_sel:[1,0] op_sel_hi:[0,1]
	v_pk_fma_f32 v[4:5], v[0:1], v[0:1], v[4:5] op_sel_hi:[1,0,1]
	v_pk_mul_f32 v[6:7], v[2:3], v[132:133] op_sel:[0,1] op_sel_hi:[1,0]
	v_pk_mul_f32 v[8:9], v[2:3], v[190:191] op_sel:[0,1] op_sel_hi:[1,0]
	v_pk_mul_f32 v[2:3], v[2:3], v[4:5] op_sel:[0,1] op_sel_hi:[1,0]
	v_pk_fma_f32 v[26:27], v[0:1], v[132:133], v[6:7] op_sel_hi:[0,1,1]
	v_pk_fma_f32 v[30:31], v[0:1], v[190:191], v[8:9] op_sel_hi:[0,1,1]
	v_xor_b32_e32 v6, 0x80000000, v5
	v_mov_b32_e32 v7, v5
	v_pk_fma_f32 v[8:9], v[0:1], v[4:5], v[2:3] op_sel_hi:[0,1,1]
	v_pk_mul_f32 v[0:1], v[6:7], v[134:135] op_sel:[0,1] op_sel_hi:[1,0]
	v_pk_mul_f32 v[2:3], v[6:7], v[124:125] op_sel:[0,1] op_sel_hi:[1,0]
	v_xor_b32_e32 v6, 0x80000000, v9
	v_mov_b32_e32 v7, v9
	v_pk_fma_f32 v[0:1], v[4:5], v[134:135], v[0:1] op_sel_hi:[0,1,1]
	v_pk_fma_f32 v[4:5], v[4:5], v[124:125], v[2:3] op_sel_hi:[0,1,1]
	v_pk_mul_f32 v[2:3], v[188:189], v[6:7] op_sel:[1,0] op_sel_hi:[0,1]
	v_pk_mul_f32 v[6:7], v[6:7], v[114:115] op_sel:[0,1] op_sel_hi:[1,0]
	v_pk_fma_f32 v[2:3], v[188:189], v[8:9], v[2:3] op_sel_hi:[1,0,1]
	ds_write_b128 v169, v[24:27]
	ds_write_b128 v170, v[28:31]
	v_pk_fma_f32 v[6:7], v[8:9], v[114:115], v[6:7] op_sel_hi:[0,1,1]
	ds_write_b128 v169, v[0:3] offset:16
	ds_write_b128 v170, v[4:7] offset:16
	s_waitcnt lgkmcnt(0)
	s_barrier
	s_cbranch_scc0 .LBB0_1393
	ds_read2st64_b64 v[0:3], v145 offset1:8
	ds_read2st64_b64 v[4:7], v145 offset0:64 offset1:72
	ds_read_b64 v[118:119], v33
	ds_read_b64 v[120:121], v146
	ds_read_b64 v[122:123], v148
	ds_read_b64 v[124:125], v149
	ds_read2st64_b64 v[8:11], v145 offset0:16 offset1:24
	ds_read2st64_b64 v[12:15], v145 offset0:80 offset1:88
	ds_read_b64 v[126:127], v151
	ds_read_b64 v[128:129], v152
	ds_read_b64 v[130:131], v154
	ds_read_b64 v[132:133], v155
	ds_read2st64_b64 v[16:19], v145 offset0:32 offset1:40
	ds_read2st64_b64 v[20:23], v145 offset0:96 offset1:104
	ds_read_b64 v[134:135], v156
	ds_read_b64 v[136:137], v157
	ds_read_b64 v[138:139], v158
	ds_read_b64 v[140:141], v159
	ds_read2st64_b64 v[24:27], v145 offset0:48 offset1:56
	ds_read2st64_b64 v[28:31], v145 offset0:112 offset1:120
	ds_read_b64 v[142:143], v160
	ds_read_b64 v[184:185], v161
	ds_read_b64 v[186:187], v162
	ds_read_b64 v[188:189], v163
	s_waitcnt lgkmcnt(14)
	v_pk_add_f32 v[112:113], v[0:1], v[4:5]
	v_pk_add_f32 v[114:115], v[0:1], v[4:5] neg_lo:[0,1] neg_hi:[0,1]
	v_pk_add_f32 v[0:1], v[2:3], v[6:7]
	v_pk_add_f32 v[2:3], v[2:3], v[6:7] neg_lo:[0,1] neg_hi:[0,1]
	s_waitcnt lgkmcnt(0)
	s_barrier
	v_pk_add_f32 v[116:117], v[118:119], v[120:121]
	v_pk_add_f32 v[118:119], v[118:119], v[120:121] neg_lo:[0,1] neg_hi:[0,1]
	ds_write_b128 v171, v[112:115]
	ds_write_b128 v172, v[116:119]
	v_pk_add_f32 v[4:5], v[122:123], v[124:125]
	v_pk_add_f32 v[6:7], v[122:123], v[124:125] neg_lo:[0,1] neg_hi:[0,1]
	ds_write_b128 v171, v[0:3] offset:8192
	ds_write_b128 v173, v[4:7]
	v_pk_add_f32 v[0:1], v[8:9], v[12:13]
	v_pk_add_f32 v[2:3], v[8:9], v[12:13] neg_lo:[0,1] neg_hi:[0,1]
	v_pk_add_f32 v[4:5], v[126:127], v[128:129]
	v_pk_add_f32 v[6:7], v[126:127], v[128:129] neg_lo:[0,1] neg_hi:[0,1]
	ds_write_b128 v171, v[0:3] offset:16384
	ds_write_b128 v174, v[4:7]
	v_pk_add_f32 v[0:1], v[10:11], v[14:15]
	v_pk_add_f32 v[2:3], v[10:11], v[14:15] neg_lo:[0,1] neg_hi:[0,1]
	v_pk_add_f32 v[4:5], v[130:131], v[132:133]
	v_pk_add_f32 v[6:7], v[130:131], v[132:133] neg_lo:[0,1] neg_hi:[0,1]
	ds_write_b128 v171, v[0:3] offset:24576
	ds_write_b128 v175, v[4:7]
	v_pk_add_f32 v[0:1], v[16:17], v[20:21]
	v_pk_add_f32 v[2:3], v[16:17], v[20:21] neg_lo:[0,1] neg_hi:[0,1]
	v_pk_add_f32 v[4:5], v[134:135], v[136:137]
	v_pk_add_f32 v[6:7], v[134:135], v[136:137] neg_lo:[0,1] neg_hi:[0,1]
	ds_write_b128 v171, v[0:3] offset:32768
	ds_write_b128 v176, v[4:7]
	v_pk_add_f32 v[0:1], v[18:19], v[22:23]
	v_pk_add_f32 v[2:3], v[18:19], v[22:23] neg_lo:[0,1] neg_hi:[0,1]
	v_pk_add_f32 v[4:5], v[138:139], v[140:141]
	v_pk_add_f32 v[6:7], v[138:139], v[140:141] neg_lo:[0,1] neg_hi:[0,1]
	ds_write_b128 v171, v[0:3] offset:40960
	ds_write_b128 v177, v[4:7]
	v_pk_add_f32 v[0:1], v[24:25], v[28:29]
	v_pk_add_f32 v[2:3], v[24:25], v[28:29] neg_lo:[0,1] neg_hi:[0,1]
	v_pk_add_f32 v[4:5], v[142:143], v[184:185]
	v_pk_add_f32 v[6:7], v[142:143], v[184:185] neg_lo:[0,1] neg_hi:[0,1]
	ds_write_b128 v171, v[0:3] offset:49152
	ds_write_b128 v178, v[4:7]
	v_pk_add_f32 v[0:1], v[26:27], v[30:31]
	v_pk_add_f32 v[2:3], v[26:27], v[30:31] neg_lo:[0,1] neg_hi:[0,1]
	v_pk_add_f32 v[4:5], v[186:187], v[188:189]
	v_pk_add_f32 v[6:7], v[186:187], v[188:189] neg_lo:[0,1] neg_hi:[0,1]
	ds_write_b128 v171, v[0:3] offset:57344
	ds_write_b128 v179, v[4:7]
	v_and_b32_e32 v2, 0xff, v32
	v_lshrrev_b32_e32 v0, 8, v32
	v_lshlrev_b32_e32 v2, 1, v2
	v_lshl_or_b32 v2, v0, 12, v2
	s_waitcnt lgkmcnt(0)
	s_barrier
	s_mov_b32 s40, 0
	v_lshlrev_b32_e32 v3, 5, v2
	v_lshlrev_b32_e32 v4, 9, v2
	v_lshlrev_b32_e32 v5, 12, v2
	v_lshrrev_b32_e32 v0, 3, v2
	v_lshlrev_b32_e32 v1, 1, v2
	v_and_b32_e32 v3, 0x300, v3
	v_and_b32_e32 v4, 0xc00, v4
	v_and_b32_e32 v5, 0x1000, v5
	v_and_b32_e32 v0, 48, v0
	v_and_b32_e32 v1, 0xc0, v1
	v_or3_b32 v3, v4, v5, v3
	v_or3_b32 v3, v3, v1, v0
	v_lshl_add_u32 v4, v2, 3, 0
	s_branch .LBB0_1396

.LBB0_1411:
	s_sub_i32 s1, 0, s0
	v_add_u32_e32 v96, 0, v144
	v_and_b32_e32 v128, s1, v32
	v_add_u32_e32 v124, 0x10000, v96
	v_and_b32_e32 v129, s1, v147
	v_lshl_add_u32 v128, v128, 3, s29
	ds_read_b128 v[96:99], v124
	ds_read_b128 v[100:103], v124 offset:16
	ds_read_b128 v[104:107], v124 offset:16384
	ds_read_b128 v[108:111], v124 offset:16400
	ds_read_b128 v[112:115], v124 offset:32768
	ds_read_b128 v[116:119], v124 offset:32784
	ds_read_b128 v[120:123], v124 offset:49152
	ds_read_b128 v[124:127], v124 offset:49168
	v_lshl_add_u32 v136, v129, 3, s29
	v_and_b32_e32 v130, s1, v150
	v_and_b32_e32 v131, s1, v153
	v_lshl_add_u32 v137, v130, 3, s29
	v_lshl_add_u32 v138, v131, 3, s29
	ds_read_b64 v[128:129], v128
	ds_read_b64 v[200:201], v136
	ds_read_b64 v[202:203], v137
	ds_read_b64 v[204:205], v138
	s_waitcnt lgkmcnt(0)
	v_xor_b32_e32 v130, 0x80000000, v129
	v_mov_b32_e32 v131, v129
	v_mov_b32_e32 v132, v129
	v_pk_mul_f32 v[134:135], v[128:129], v[130:131] op_sel:[1,0] op_sel_hi:[0,1]
	v_mov_b32_e32 v133, v130
	v_pk_fma_f32 v[134:135], v[128:129], v[128:129], v[134:135] op_sel_hi:[1,0,1]
	v_pk_mul_f32 v[132:133], v[98:99], v[132:133] op_sel:[1,0] op_sel_hi:[0,1]
	v_pk_mul_f32 v[130:131], v[130:131], v[134:135] op_sel:[0,1] op_sel_hi:[1,0]
	v_pk_fma_f32 v[98:99], v[128:129], v[98:99], v[132:133] op_sel_hi:[0,1,1]
	v_pk_add_f32 v[132:133], v[134:135], 0 neg_lo:[1,1] neg_hi:[1,1]
	v_pk_fma_f32 v[128:129], v[128:129], v[134:135], v[130:131] op_sel_hi:[0,1,1]
	v_mov_b32_e32 v132, v135
	v_pk_mul_f32 v[130:131], v[100:101], v[132:133] op_sel:[1,0] op_sel_hi:[0,1]
	v_pk_add_f32 v[132:133], v[128:129], 0 neg_lo:[1,1] neg_hi:[1,1]
	v_pk_fma_f32 v[100:101], v[100:101], v[134:135], v[130:131] op_sel_hi:[1,0,1]
	v_mov_b32_e32 v132, v129
	v_pk_mul_f32 v[130:131], v[102:103], v[132:133] op_sel:[1,0] op_sel_hi:[0,1]
	v_pk_add_f32 v[132:133], v[96:97], v[100:101]
	v_pk_add_f32 v[96:97], v[96:97], v[100:101] neg_lo:[0,1] neg_hi:[0,1]
	v_pk_fma_f32 v[100:101], v[102:103], v[128:129], v[130:131] op_sel_hi:[1,0,1]
	s_lshr_b32 s4, s0, 2
	v_pk_add_f32 v[102:103], v[98:99], v[100:101]
	v_pk_add_f32 v[98:99], v[98:99], v[100:101] neg_lo:[0,1] neg_hi:[0,1]
	v_pk_add_f32 v[100:101], v[132:133], v[102:103]
	v_pk_mul_f32 v[98:99], v[98:99], s[58:59]
	v_pk_add_f32 v[102:103], v[132:133], v[102:103] neg_lo:[0,1] neg_hi:[0,1]
	v_pk_add_f32 v[128:129], v[96:97], v[98:99] op_sel:[0,1] op_sel_hi:[1,0] neg_lo:[0,1] neg_hi:[0,1]
	v_pk_add_f32 v[96:97], v[96:97], v[98:99] op_sel:[0,1] op_sel_hi:[1,0]
	s_barrier
	ds_write2st64_b64 v33, v[100:101], v[128:129] offset1:32
	ds_write2st64_b64 v33, v[102:103], v[96:97] offset0:64 offset1:96
	v_mov_b64_e32 v[96:97], v[200:201]
	s_cmp_lt_u32 s0, 4
	s_mov_b32 s0, s4
	v_xor_b32_e32 v98, 0x80000000, v97
	v_mov_b32_e32 v99, v97
	v_mov_b32_e32 v100, v97
	v_pk_mul_f32 v[102:103], v[96:97], v[98:99] op_sel:[1,0] op_sel_hi:[0,1]
	v_mov_b32_e32 v101, v98
	v_pk_fma_f32 v[102:103], v[96:97], v[96:97], v[102:103] op_sel_hi:[1,0,1]
	v_pk_mul_f32 v[100:101], v[106:107], v[100:101] op_sel:[1,0] op_sel_hi:[0,1]
	v_pk_mul_f32 v[98:99], v[98:99], v[102:103] op_sel:[0,1] op_sel_hi:[1,0]
	v_pk_fma_f32 v[100:101], v[96:97], v[106:107], v[100:101] op_sel_hi:[0,1,1]
	v_pk_add_f32 v[106:107], v[102:103], 0 neg_lo:[1,1] neg_hi:[1,1]
	v_pk_fma_f32 v[96:97], v[96:97], v[102:103], v[98:99] op_sel_hi:[0,1,1]
	v_mov_b32_e32 v106, v103
	v_pk_mul_f32 v[98:99], v[108:109], v[106:107] op_sel:[1,0] op_sel_hi:[0,1]
	v_pk_add_f32 v[106:107], v[96:97], 0 neg_lo:[1,1] neg_hi:[1,1]
	v_pk_fma_f32 v[98:99], v[108:109], v[102:103], v[98:99] op_sel_hi:[1,0,1]
	v_mov_b32_e32 v106, v97
	v_pk_mul_f32 v[102:103], v[110:111], v[106:107] op_sel:[1,0] op_sel_hi:[0,1]
	v_pk_fma_f32 v[96:97], v[110:111], v[96:97], v[102:103] op_sel_hi:[1,0,1]
	v_pk_add_f32 v[106:107], v[104:105], v[98:99]
	v_pk_add_f32 v[102:103], v[100:101], v[96:97]
	v_pk_add_f32 v[96:97], v[100:101], v[96:97] neg_lo:[0,1] neg_hi:[0,1]
	v_pk_add_f32 v[98:99], v[104:105], v[98:99] neg_lo:[0,1] neg_hi:[0,1]
	v_pk_mul_f32 v[96:97], v[96:97], s[58:59]
	v_pk_add_f32 v[100:101], v[106:107], v[102:103]
	v_pk_add_f32 v[104:105], v[98:99], v[96:97] op_sel:[0,1] op_sel_hi:[1,0] neg_lo:[0,1] neg_hi:[0,1]
	v_pk_add_f32 v[102:103], v[106:107], v[102:103] neg_lo:[0,1] neg_hi:[0,1]
	v_pk_add_f32 v[96:97], v[98:99], v[96:97] op_sel:[0,1] op_sel_hi:[1,0]
	ds_write2st64_b64 v148, v[100:101], v[104:105] offset1:32
	ds_write2st64_b64 v148, v[102:103], v[96:97] offset0:64 offset1:96
	v_mov_b64_e32 v[96:97], v[202:203]
	v_xor_b32_e32 v98, 0x80000000, v97
	v_mov_b32_e32 v99, v97
	v_pk_mul_f32 v[102:103], v[96:97], v[98:99] op_sel:[1,0] op_sel_hi:[0,1]
	v_mov_b32_e32 v100, v97
	v_mov_b32_e32 v101, v98
	v_pk_fma_f32 v[102:103], v[96:97], v[96:97], v[102:103] op_sel_hi:[1,0,1]
	v_pk_mul_f32 v[100:101], v[114:115], v[100:101] op_sel:[1,0] op_sel_hi:[0,1]
	v_pk_mul_f32 v[98:99], v[98:99], v[102:103] op_sel:[0,1] op_sel_hi:[1,0]
	v_pk_add_f32 v[104:105], v[102:103], 0 neg_lo:[1,1] neg_hi:[1,1]
	v_pk_fma_f32 v[100:101], v[96:97], v[114:115], v[100:101] op_sel_hi:[0,1,1]
	v_pk_fma_f32 v[96:97], v[96:97], v[102:103], v[98:99] op_sel_hi:[0,1,1]
	v_mov_b32_e32 v104, v103
	v_pk_mul_f32 v[98:99], v[116:117], v[104:105] op_sel:[1,0] op_sel_hi:[0,1]
	v_pk_add_f32 v[104:105], v[96:97], 0 neg_lo:[1,1] neg_hi:[1,1]
	v_pk_fma_f32 v[98:99], v[116:117], v[102:103], v[98:99] op_sel_hi:[1,0,1]
	v_mov_b32_e32 v104, v97
	v_pk_mul_f32 v[102:103], v[118:119], v[104:105] op_sel:[1,0] op_sel_hi:[0,1]
	v_pk_fma_f32 v[96:97], v[118:119], v[96:97], v[102:103] op_sel_hi:[1,0,1]
	v_pk_add_f32 v[104:105], v[112:113], v[98:99]
	v_pk_add_f32 v[102:103], v[100:101], v[96:97]
	v_pk_add_f32 v[96:97], v[100:101], v[96:97] neg_lo:[0,1] neg_hi:[0,1]
	v_pk_add_f32 v[98:99], v[112:113], v[98:99] neg_lo:[0,1] neg_hi:[0,1]
	v_pk_mul_f32 v[96:97], v[96:97], s[58:59]
	v_pk_add_f32 v[100:101], v[104:105], v[102:103]
	v_pk_add_f32 v[102:103], v[104:105], v[102:103] neg_lo:[0,1] neg_hi:[0,1]
	v_pk_add_f32 v[104:105], v[98:99], v[96:97] op_sel:[0,1] op_sel_hi:[1,0] neg_lo:[0,1] neg_hi:[0,1]
	v_pk_add_f32 v[96:97], v[98:99], v[96:97] op_sel:[0,1] op_sel_hi:[1,0]
	ds_write2st64_b64 v151, v[100:101], v[104:105] offset1:32
	ds_write2st64_b64 v151, v[102:103], v[96:97] offset0:64 offset1:96
	v_mov_b64_e32 v[96:97], v[204:205]
	v_xor_b32_e32 v98, 0x80000000, v97
	v_mov_b32_e32 v99, v97
	v_pk_mul_f32 v[102:103], v[96:97], v[98:99] op_sel:[1,0] op_sel_hi:[0,1]
	v_mov_b32_e32 v100, v97
	v_mov_b32_e32 v101, v98
	v_pk_fma_f32 v[102:103], v[96:97], v[96:97], v[102:103] op_sel_hi:[1,0,1]
	v_pk_mul_f32 v[100:101], v[122:123], v[100:101] op_sel:[1,0] op_sel_hi:[0,1]
	v_pk_mul_f32 v[98:99], v[98:99], v[102:103] op_sel:[0,1] op_sel_hi:[1,0]
	v_pk_add_f32 v[104:105], v[102:103], 0 neg_lo:[1,1] neg_hi:[1,1]
	v_pk_fma_f32 v[100:101], v[96:97], v[122:123], v[100:101] op_sel_hi:[0,1,1]
	v_pk_fma_f32 v[96:97], v[96:97], v[102:103], v[98:99] op_sel_hi:[0,1,1]
	v_mov_b32_e32 v104, v103
	v_pk_mul_f32 v[98:99], v[124:125], v[104:105] op_sel:[1,0] op_sel_hi:[0,1]
	v_pk_add_f32 v[104:105], v[96:97], 0 neg_lo:[1,1] neg_hi:[1,1]
	v_pk_fma_f32 v[98:99], v[124:125], v[102:103], v[98:99] op_sel_hi:[1,0,1]
	v_mov_b32_e32 v104, v97
	v_pk_mul_f32 v[102:103], v[126:127], v[104:105] op_sel:[1,0] op_sel_hi:[0,1]
	v_pk_fma_f32 v[96:97], v[126:127], v[96:97], v[102:103] op_sel_hi:[1,0,1]
	v_pk_add_f32 v[104:105], v[120:121], v[98:99]
	v_pk_add_f32 v[102:103], v[100:101], v[96:97]
	v_pk_add_f32 v[96:97], v[100:101], v[96:97] neg_lo:[0,1] neg_hi:[0,1]
	v_pk_add_f32 v[98:99], v[120:121], v[98:99] neg_lo:[0,1] neg_hi:[0,1]
	v_pk_mul_f32 v[96:97], v[96:97], s[58:59]
	v_pk_add_f32 v[100:101], v[104:105], v[102:103]
	v_pk_add_f32 v[102:103], v[104:105], v[102:103] neg_lo:[0,1] neg_hi:[0,1]
	v_pk_add_f32 v[104:105], v[98:99], v[96:97] op_sel:[0,1] op_sel_hi:[1,0] neg_lo:[0,1] neg_hi:[0,1]
	v_pk_add_f32 v[96:97], v[98:99], v[96:97] op_sel:[0,1] op_sel_hi:[1,0]
	ds_write2st64_b64 v154, v[100:101], v[104:105] offset1:32
	ds_write2st64_b64 v154, v[102:103], v[96:97] offset0:64 offset1:96
	s_waitcnt lgkmcnt(0)
	s_barrier
	s_cbranch_scc0 .LBB0_1411
	s_lshl_b64 s[0:1], s[68:69], 2
	s_add_u32 s0, s24, s0
	s_addc_u32 s1, s23, s1
	v_mov_b64_e32 v[96:97], s[0:1]
	flat_load_dword v96, v[96:97]
	ds_read_b64 v[98:99], v33
	ds_read_b64 v[100:101], v148
	ds_read_b64 v[102:103], v151
	ds_read_b64 v[104:105], v154
	ds_read_b64 v[106:107], v156
	ds_read_b64 v[108:109], v158
	ds_read_b64 v[110:111], v160
	ds_read_b64 v[112:113], v162
	s_add_u32 s0, s48, s20
	s_addc_u32 s1, s49, s21
	s_add_i32 s68, s68, s30
	v_lshl_add_u64 v[114:115], v[34:35], 2, s[0:1]
	s_cmpk_gt_i32 s68, 0x7ff
	v_lshl_add_u64 v[116:117], v[82:83], 2, s[0:1]
	v_lshl_add_u64 v[118:119], v[84:85], 2, s[0:1]
	v_lshl_add_u64 v[120:121], v[86:87], 2, s[0:1]
	v_lshl_add_u64 v[122:123], v[88:89], 2, s[0:1]
	v_lshl_add_u64 v[124:125], v[90:91], 2, s[0:1]
	v_lshl_add_u64 v[126:127], v[92:93], 2, s[0:1]
	v_lshl_add_u64 v[128:129], v[94:95], 2, s[0:1]
	s_waitcnt vmcnt(0) lgkmcnt(0)
	v_pk_mul_f32 v[8:9], v[96:97], v[8:9] op_sel_hi:[0,1]
	v_pk_mul_f32 v[10:11], v[96:97], v[10:11] op_sel_hi:[0,1]
	v_pk_mul_f32 v[12:13], v[96:97], v[12:13] op_sel_hi:[0,1]
	v_pk_mul_f32 v[14:15], v[96:97], v[14:15] op_sel_hi:[0,1]
	v_pk_mul_f32 v[24:25], v[96:97], v[24:25] op_sel_hi:[0,1]
	v_pk_mul_f32 v[26:27], v[96:97], v[26:27] op_sel_hi:[0,1]
	v_pk_mul_f32 v[28:29], v[96:97], v[28:29] op_sel_hi:[0,1]
	v_pk_mul_f32 v[30:31], v[96:97], v[30:31] op_sel_hi:[0,1]
	v_pk_fma_f32 v[8:9], v[98:99], s[66:67], v[8:9] op_sel_hi:[1,0,1]
	v_pk_fma_f32 v[10:11], v[100:101], s[66:67], v[10:11] op_sel_hi:[1,0,1]
	v_pk_fma_f32 v[12:13], v[102:103], s[66:67], v[12:13] op_sel_hi:[1,0,1]
	v_pk_fma_f32 v[14:15], v[104:105], s[66:67], v[14:15] op_sel_hi:[1,0,1]
	v_pk_fma_f32 v[24:25], v[106:107], s[66:67], v[24:25] op_sel_hi:[1,0,1]
	v_pk_fma_f32 v[26:27], v[108:109], s[66:67], v[26:27] op_sel_hi:[1,0,1]
	v_pk_fma_f32 v[28:29], v[110:111], s[66:67], v[28:29] op_sel_hi:[1,0,1]
	v_pk_fma_f32 v[30:31], v[112:113], s[66:67], v[30:31] op_sel_hi:[1,0,1]
	v_pk_mul_f32 v[0:1], v[0:1], v[8:9]
	v_pk_mul_f32 v[2:3], v[2:3], v[10:11]
	v_pk_mul_f32 v[4:5], v[4:5], v[12:13]
	v_pk_mul_f32 v[6:7], v[6:7], v[14:15]
	v_pk_mul_f32 v[8:9], v[16:17], v[24:25]
	v_pk_mul_f32 v[10:11], v[18:19], v[26:27]
	v_pk_mul_f32 v[12:13], v[20:21], v[28:29]
	v_pk_mul_f32 v[14:15], v[22:23], v[30:31]
	global_store_dwordx2 v[114:115], v[0:1], off
	global_store_dwordx2 v[116:117], v[2:3], off
	global_store_dwordx2 v[118:119], v[4:5], off
	global_store_dwordx2 v[120:121], v[6:7], off
	global_store_dwordx2 v[122:123], v[8:9], off
	global_store_dwordx2 v[124:125], v[10:11], off
	global_store_dwordx2 v[126:127], v[12:13], off
	global_store_dwordx2 v[128:129], v[14:15], off
	s_barrier
	s_cbranch_scc0 .LBB0_1376
